# P4: workgroups 0-63 take 14 B/C units (rest 17) plus one static s_setprio 1 for waves 0-3 during the attention phase
# speedup vs baseline: 1.0017x; 1.0017x over previous
; #define LAS __attribute__((address_space(3)))
; __global__ void __launch_bounds__(512, 2) fwd_kernel(Args a) {
;     ...
;         {
;           AttnP P{R, YA, YB, YC, a.t5, a.rpb + (size_t)l * 8 * 465, a.sink + l * 8, a.subg + l * 128, a.lq1 + l * 64, a.lk1 + l * 64, a.lq2 + l * 64, a.lk2 + l * 64,
;                   l};
;           for (int rep = 0; rep < ATT_REPS; ++rep) {
;           if (G == 256) { const int x = blockIdx.x & 7, jx = blockIdx.x >> 3;
;               for (int r = 0; r < 8; ++r) attn_unit_A(P, (x + 8 * r) * 33 + jx, (LAS char*)lds);
;               if (jx < 8) attn_unit_A(P, (x + 8 * jx) * 33 + 32, (LAS char*)lds);
;           } else { for (int u = blockIdx.x; u < NUA; u += G) attn_unit_A(P, u, (LAS char*)lds); }
.LBB0_526:
	s_or_b64 exec, exec, s[0:1]
	s_lshl_b32 s80, s60, 7
	v_readlane_b32 s52, v252, 4
	s_lshl_b64 s[0:1], s[80:81], 2
	v_readlane_b32 s60, v252, 12
	v_readlane_b32 s62, v252, 14
	v_readlane_b32 s63, v252, 15
	v_readlane_b32 s61, v252, 13
	v_readlane_b32 s62, v255, 46
	s_add_u32 s46, s60, s0
	s_addc_u32 s47, s61, s1
	s_lshl_b32 s80, s62, 6
	s_lshl_b64 s[0:1], s[80:81], 2
	v_readlane_b32 s53, v252, 5
	s_add_u32 s48, s52, s0
	v_readlane_b32 s54, v252, 6
	s_addc_u32 s49, s53, s1
	v_readlane_b32 s55, v252, 7
	s_add_u32 s42, s54, s0
	v_readlane_b32 s56, v252, 8
	s_addc_u32 s43, s55, s1
	v_readlane_b32 s57, v252, 9
	s_add_u32 s52, s56, s0
	v_readlane_b32 s58, v252, 10
	s_addc_u32 s53, s57, s1
	v_readlane_b32 s59, v252, 11
	s_add_u32 s54, s58, s0
	s_addc_u32 s55, s59, s1
	s_cmp_eq_u32 s62, 2
	v_readlane_b32 s12, v253, 54
	s_cselect_b64 vcc, -1, 0
	v_mov_b32_e32 v0, 0x3f0e59d5
	s_waitcnt lgkmcnt(0)
	v_mov_b32_e32 v2, 0x3ef1014c
	v_readlane_b32 s13, v253, 55
	v_cndmask_b32_e32 v164, v0, v2, vcc
	s_mov_b64 s[0:1], -1
	s_and_b64 vcc, exec, s[12:13]
	s_mov_b32 s56, 0x3fb8aa3b
	s_barrier
	v_writelane_b32 v255, s40, 61
	v_readfirstlane_b32 s40, v234
	s_nop 3
	s_cmpk_ge_u32 s40, 0x100
	v_readlane_b32 s40, v255, 61
	s_cbranch_scc1 .Lp4prio_skip
	s_setprio 1
.Lp4prio_skip:
	v_readlane_b32 s64, v252, 16
	v_readlane_b32 s65, v252, 17
	v_readlane_b32 s66, v252, 18
	v_readlane_b32 s67, v252, 19
	v_readlane_b32 s63, v255, 47
	s_cbranch_vccz .LBB0_623
	v_readlane_b32 s0, v253, 56
	v_readlane_b32 s1, v253, 57
	s_andn2_b64 vcc, exec, s[0:1]
	s_cbranch_vccnz .LBB0_622
	s_mov_b32 s12, s2
	s_branch .LBB0_531

; __device__ __forceinline__ void xcd_barrier(const XcdBarrier& b) {
;     asm volatile("s_waitcnt vmcnt(0)" ::: "memory");
;     __syncthreads();
;     if (threadIdx.x == 0) {
;         unsigned* bar = b.bar;
;         __builtin_amdgcn_s_waitcnt(0);
;         unsigned nloc = b.st[0], nx = b.st[1];
;         if (nloc == 0u) { xcd_barrier_complete(bar, b.x, nloc, nx); b.st[0] = nloc; b.st[1] = nx; }
.LBB0_1373:
	s_waitcnt vmcnt(0)
	s_setprio 0
	s_barrier
	s_mov_b64 s[0:1], exec
	v_readlane_b32 s12, v252, 2
	v_readlane_b32 s13, v252, 3
	s_and_b64 s[12:13], s[0:1], s[12:13]
	s_xor_b64 s[0:1], s[12:13], s[0:1]
	s_mov_b32 s54, 0x10000
	v_readlane_b32 s64, v255, 46
	v_readlane_b32 s96, v255, 45
	v_readlane_b32 s65, v255, 47
	s_mov_b64 exec, s[12:13]
	s_cbranch_execz .LBB0_1426
	v_readlane_b32 s12, v255, 17
	s_waitcnt vmcnt(0) expcnt(0) lgkmcnt(0)
	s_nop 0
	v_mov_b32_e32 v0, s12
	ds_read_b32 v3, v0
	v_readlane_b32 s12, v255, 18
	s_waitcnt lgkmcnt(0)
	v_cmp_ne_u32_e32 vcc, 0, v3
	v_mov_b32_e32 v0, s12
	ds_read_b32 v2, v0
	s_cbranch_vccnz .LBB0_1389
	s_mov_b32 s12, 1
	s_branch .LBB0_1377
